# rows0 (layer-0 pre-mix norm) row loop software-pipelined by one row, two register sets; DPP hazard fillers restored
# baseline (speedup 1.0000x reference)
.LBB0_156:
	s_or_b64 exec, exec, s[2:3]
	s_waitcnt lgkmcnt(0)
	v_mov_b32_e32 v0, v156
	s_mov_b32 s2, s92
	s_barrier
	v_mbcnt_lo_u32_b32 v76, -1, 0
	v_ashrrev_i32_e32 v1, 6, v0
	v_lshl_add_u32 v64, s2, 3, v1
	s_movk_i32 s2, 0x4200
	v_cmp_gt_i32_e32 vcc, s2, v64
	s_and_saveexec_b64 s[2:3], vcc
	s_cbranch_execz .LBB0_161
	s_load_dwordx2 s[4:5], s[0:1], 0x30
	s_load_dwordx2 s[6:7], s[0:1], 0x108
	v_lshlrev_b32_e32 v0, 2, v0
	v_and_b32_e32 v16, 0xfc, v0
	v_lshlrev_b32_e32 v17, 2, v16
	s_waitcnt lgkmcnt(0)
	global_load_dwordx4 v[0:3], v17, s[4:5]
	global_load_dwordx4 v[4:7], v17, s[4:5] offset:1024
	global_load_dwordx4 v[8:11], v17, s[4:5] offset:2048
	global_load_dwordx4 v[12:15], v17, s[4:5] offset:3072
	s_load_dwordx2 s[10:11], s[0:1], 0x0
	s_load_dwordx2 s[16:17], s[0:1], 0x10
	v_mbcnt_hi_u32_b32 v17, -1, v76
	v_and_b32_e32 v21, 64, v17
	v_xor_b32_e32 v19, 16, v17
	v_add_u32_e32 v21, 64, v21
	s_add_u32 s4, s6, 0x10000
	v_mov_b32_e32 v67, 0
	v_cmp_lt_i32_e32 vcc, v19, v21
	v_lshlrev_b32_e32 v66, 1, v16
	s_addc_u32 s5, s7, 0
	v_or_b32_e32 v18, 0x100, v16
	v_or_b32_e32 v20, 0x200, v16
	v_or_b32_e32 v22, 0x300, v16
	v_cndmask_b32_e32 v17, v17, v19, vcc
	v_lshl_add_u64 v[24:25], s[6:7], 0, v[66:67]
	s_mov_b64 s[6:7], 0x1b20000
	v_mov_b32_e32 v26, v67
	v_mov_b32_e32 v27, v67
	s_lshl_b32 s12, s28, 3
	v_mov_b32_e32 v71, -1
	v_lshlrev_b32_e32 v77, 2, v17
	v_lshl_add_u64 v[68:69], v[24:25], 0, s[6:7]
	s_mov_b64 s[6:7], 0
	s_movk_i32 s13, 0x4000
	s_mov_b64 s[8:9], 0x1000
	v_lshlrev_b32_e32 v70, 2, v18
	v_lshlrev_b32_e32 v72, 2, v20
	v_lshlrev_b32_e32 v74, 2, v22
	v_mov_b32_e32 v78, 0x358637bd
	s_movk_i32 s14, 0x41ff
	s_waitcnt lgkmcnt(0)
	v_mov_b32_e32 v79, s17
	v_mov_b32_e32 v80, s11
	v_mov_b32_e32 v81, s16
	v_mov_b32_e32 v82, s10
	v_lshlrev_b32_e32 v66, 2, v16
	v_mov_b64_e32 v[24:25], v[26:27]
	v_mov_b64_e32 v[38:39], v[26:27]
	v_mov_b64_e32 v[36:37], v[26:27]
	v_mov_b64_e32 v[42:43], v[26:27]
	v_mov_b64_e32 v[40:41], v[26:27]
	v_mov_b64_e32 v[18:19], v[26:27]
	v_mov_b64_e32 v[16:17], v[26:27]
	v_mov_b64_e32 v[46:47], v[26:27]
	v_mov_b64_e32 v[44:45], v[26:27]
	v_mov_b64_e32 v[34:35], v[26:27]
	v_mov_b64_e32 v[32:33], v[26:27]
	v_mov_b64_e32 v[30:31], v[26:27]
	v_mov_b64_e32 v[28:29], v[26:27]
	v_mov_b64_e32 v[22:23], v[26:27]
	v_mov_b64_e32 v[20:21], v[26:27]
	v_mov_b32_e32 v65, 0
	v_add_u32_e32 v48, 0xffffc000, v64
	v_ashrrev_i32_e32 v65, 31, v64
	v_cmp_gt_i32_e32 vcc, s13, v64
	v_min_i32_e32 v73, 0x4000, v64
	v_ashrrev_i32_e32 v83, 13, v73
	v_cndmask_b32_e32 v49, 0, v65, vcc
	v_cndmask_b32_e32 v48, v48, v64, vcc
	v_cndmask_b32_e32 v51, v79, v80, vcc
	v_cndmask_b32_e32 v50, v81, v82, vcc
	v_lshlrev_b64 v[48:49], 12, v[48:49]
	v_lshl_add_u64 v[48:49], v[50:51], 0, v[48:49]
	v_lshl_add_u64 v[84:85], v[48:49], 0, v[66:67]
	global_load_dwordx4 v[60:63], v[84:85], off nt
	global_load_dwordx4 v[56:59], v[84:85], off offset:1024 nt
	global_load_dwordx4 v[52:55], v[84:85], off offset:2048 nt
	global_load_dwordx4 v[48:51], v[84:85], off offset:3072 nt
	s_mov_b32 s10, 0
.Lr0_A:
	v_cmp_ne_u32_e32 vcc, v83, v71
	s_mov_b32 s11, 0
	s_cbranch_vccz .Lr0_nomods_A
	v_mul_hi_i32_i24_e32 v17, 0x6000, v83
	v_mul_i32_i24_e32 v16, 0x6000, v83
	v_lshl_add_u64 v[16:17], s[4:5], 0, v[16:17]
	v_lshl_add_u64 v[24:25], v[16:17], 0, s[8:9]
	v_mov_b32_e32 v73, v67
	v_lshl_add_u64 v[26:27], v[24:25], 0, v[66:67]
	v_lshl_add_u64 v[84:85], v[16:17], 0, v[66:67]
	v_mov_b32_e32 v71, v67
	v_lshl_add_u64 v[88:89], v[24:25], 0, v[72:73]
	v_mov_b32_e32 v75, v67
	global_load_dwordx4 v[16:19], v[26:27], off
	global_load_dwordx4 v[20:23], v[84:85], off
	v_lshl_add_u64 v[86:87], v[24:25], 0, v[70:71]
	global_load_dwordx4 v[28:31], v[84:85], off offset:1024
	global_load_dwordx4 v[32:35], v[84:85], off offset:2048
	v_lshl_add_u64 v[90:91], v[24:25], 0, v[74:75]
	global_load_dwordx4 v[36:39], v[88:89], off
	global_load_dwordx4 v[24:27], v[90:91], off
	global_load_dwordx4 v[40:43], v[86:87], off
	global_load_dwordx4 v[44:47], v[84:85], off offset:3072
	v_mov_b32_e32 v71, v83
	s_mov_b32 s11, 1
.Lr0_nomods_A:
	v_add_u32_e32 v92, s12, v64
	s_nop 0
	v_readfirstlane_b32 s16, v92
	s_nop 3
	s_cmp_le_i32 s16, s14
	s_cselect_b32 s17, 1, 0
	s_cbranch_scc0 .Lr0_nonext_A
	v_add_u32_e32 v120, 0xffffc000, v92
	v_ashrrev_i32_e32 v124, 31, v92
	v_cmp_gt_i32_e32 vcc, s13, v92
	v_min_i32_e32 v125, 0x4000, v92
	v_ashrrev_i32_e32 v118, 13, v125
	v_cndmask_b32_e32 v121, 0, v124, vcc
	v_cndmask_b32_e32 v120, v120, v92, vcc
	v_cndmask_b32_e32 v123, v79, v80, vcc
	v_cndmask_b32_e32 v122, v81, v82, vcc
	v_lshlrev_b64 v[120:121], 12, v[120:121]
	v_lshl_add_u64 v[120:121], v[122:123], 0, v[120:121]
	v_lshl_add_u64 v[116:117], v[120:121], 0, v[66:67]
	global_load_dwordx4 v[112:115], v[116:117], off nt
	global_load_dwordx4 v[108:111], v[116:117], off offset:1024 nt
	global_load_dwordx4 v[104:107], v[116:117], off offset:2048 nt
	global_load_dwordx4 v[100:103], v[116:117], off offset:3072 nt
	s_cmp_lg_u32 s11, 0
	s_cbranch_scc1 .Lr0_w0_A
	s_cmp_lg_u32 s10, 0
	s_cbranch_scc1 .Lr0_w8_A
	s_waitcnt vmcnt(4)
	s_branch .Lr0_go_A
.Lr0_w8_A:
	s_waitcnt vmcnt(4)
	s_branch .Lr0_go_A
.Lr0_nonext_A:
.Lr0_w0_A:
	s_waitcnt vmcnt(0)
.Lr0_go_A:
	v_mul_f32_e32 v73, v61, v61
	v_mul_f32_e32 v75, v57, v57
	v_fmac_f32_e32 v73, v60, v60
	v_fmac_f32_e32 v75, v56, v56
	v_fmac_f32_e32 v73, v62, v62
	v_fmac_f32_e32 v75, v58, v58
	v_fmac_f32_e32 v73, v63, v63
	v_fmac_f32_e32 v75, v59, v59
	v_add_f32_e32 v73, v73, v75
	v_mul_f32_e32 v75, v53, v53
	v_fmac_f32_e32 v75, v52, v52
	v_fmac_f32_e32 v75, v54, v54
	v_fmac_f32_e32 v75, v55, v55
	v_add_f32_e32 v73, v73, v75
	v_mul_f32_e32 v75, v49, v49
	v_fmac_f32_e32 v75, v48, v48
	v_fmac_f32_e32 v75, v50, v50
	v_fmac_f32_e32 v75, v51, v51
	v_add_f32_e32 v73, v73, v75
	v_pk_add_f32 v[88:89], v[16:17], 1.0 op_sel_hi:[1,0]
	v_lshlrev_b64 v[86:87], 11, v[64:65]
	v_add_f32_dpp v73, v73, v73 row_ror:8 row_mask:0xf bank_mask:0xf bound_ctrl:1
	v_lshl_add_u64 v[86:87], v[68:69], 0, v[86:87]
	s_nop 0
	v_add_f32_dpp v73, v73, v73 row_ror:4 row_mask:0xf bank_mask:0xf bound_ctrl:1
	s_nop 0
	s_nop 0
	v_add_f32_dpp v73, v73, v73 row_ror:2 row_mask:0xf bank_mask:0xf bound_ctrl:1
	s_nop 1
	v_add_f32_dpp v73, v73, v73 row_ror:1 row_mask:0xf bank_mask:0xf bound_ctrl:1
	v_mov_b32_e32 v75, v73
	s_nop 1
	v_permlane32_swap_b32_e32 v73, v75
	v_add_f32_e32 v73, v73, v75
	ds_bpermute_b32 v75, v77, v73
	s_waitcnt lgkmcnt(0)
	v_add_f32_e32 v73, v73, v75
	v_fmamk_f32 v73, v73, 0x3a800000, v78
	v_rsq_f32_e32 v84, v73
	s_nop 0
	v_pk_mul_f32 v[60:61], v[60:61], v[84:85] op_sel_hi:[1,0]
	s_nop 0
	v_pk_mul_f32 v[60:61], v[0:1], v[60:61]
	v_pk_mul_f32 v[62:63], v[62:63], v[84:85] op_sel_hi:[1,0]
	v_pk_fma_f32 v[60:61], v[88:89], v[60:61], v[20:21]
	v_pk_mul_f32 v[62:63], v[2:3], v[62:63]
	v_pk_add_f32 v[88:89], v[18:19], 1.0 op_sel_hi:[1,0]
	v_cvt_pk_bf16_f32 v60, v60, v61
	v_pk_fma_f32 v[62:63], v[88:89], v[62:63], v[22:23]
	v_pk_mul_f32 v[56:57], v[56:57], v[84:85] op_sel_hi:[1,0]
	v_cvt_pk_bf16_f32 v61, v62, v63
	global_store_dwordx2 v[86:87], v[60:61], off
	v_pk_mul_f32 v[56:57], v[4:5], v[56:57]
	v_pk_add_f32 v[60:61], v[40:41], 1.0 op_sel_hi:[1,0]
	v_pk_mul_f32 v[58:59], v[58:59], v[84:85] op_sel_hi:[1,0]
	v_pk_fma_f32 v[56:57], v[60:61], v[56:57], v[28:29]
	v_pk_mul_f32 v[58:59], v[6:7], v[58:59]
	v_pk_add_f32 v[60:61], v[42:43], 1.0 op_sel_hi:[1,0]
	v_cvt_pk_bf16_f32 v56, v56, v57
	v_pk_fma_f32 v[58:59], v[60:61], v[58:59], v[30:31]
	v_pk_mul_f32 v[52:53], v[52:53], v[84:85] op_sel_hi:[1,0]
	v_cvt_pk_bf16_f32 v57, v58, v59
	global_store_dwordx2 v[86:87], v[56:57], off offset:512
	v_pk_mul_f32 v[52:53], v[8:9], v[52:53]
	v_pk_add_f32 v[56:57], v[36:37], 1.0 op_sel_hi:[1,0]
	v_pk_mul_f32 v[54:55], v[54:55], v[84:85] op_sel_hi:[1,0]
	v_pk_fma_f32 v[52:53], v[56:57], v[52:53], v[32:33]
	v_pk_mul_f32 v[54:55], v[10:11], v[54:55]
	v_pk_add_f32 v[56:57], v[38:39], 1.0 op_sel_hi:[1,0]
	v_cvt_pk_bf16_f32 v52, v52, v53
	v_pk_fma_f32 v[54:55], v[56:57], v[54:55], v[34:35]
	v_pk_mul_f32 v[48:49], v[48:49], v[84:85] op_sel_hi:[1,0]
	v_cvt_pk_bf16_f32 v53, v54, v55
	global_store_dwordx2 v[86:87], v[52:53], off offset:1024
	v_pk_mul_f32 v[48:49], v[12:13], v[48:49]
	v_pk_add_f32 v[52:53], v[24:25], 1.0 op_sel_hi:[1,0]
	v_pk_mul_f32 v[50:51], v[50:51], v[84:85] op_sel_hi:[1,0]
	v_pk_fma_f32 v[48:49], v[52:53], v[48:49], v[44:45]
	v_pk_mul_f32 v[50:51], v[14:15], v[50:51]
	v_pk_add_f32 v[52:53], v[26:27], 1.0 op_sel_hi:[1,0]
	v_cvt_pk_bf16_f32 v48, v48, v49
	v_pk_fma_f32 v[50:51], v[52:53], v[50:51], v[46:47]
	s_nop 0
	v_cvt_pk_bf16_f32 v49, v50, v51
	global_store_dwordx2 v[86:87], v[48:49], off offset:1536
	s_mov_b32 s10, 1
	v_mov_b32_e32 v64, v92
	v_mov_b32_e32 v83, v118
	s_cmp_lg_u32 s17, 0
	s_cbranch_scc0 .LBB0_161
	v_cmp_ne_u32_e32 vcc, v83, v71
	s_mov_b32 s11, 0
	s_cbranch_vccz .Lr0_nomods_B
	v_mul_hi_i32_i24_e32 v17, 0x6000, v83
	v_mul_i32_i24_e32 v16, 0x6000, v83
	v_lshl_add_u64 v[16:17], s[4:5], 0, v[16:17]
	v_lshl_add_u64 v[24:25], v[16:17], 0, s[8:9]
	v_mov_b32_e32 v73, v67
	v_lshl_add_u64 v[26:27], v[24:25], 0, v[66:67]
	v_lshl_add_u64 v[84:85], v[16:17], 0, v[66:67]
	v_mov_b32_e32 v71, v67
	v_lshl_add_u64 v[88:89], v[24:25], 0, v[72:73]
	v_mov_b32_e32 v75, v67
	global_load_dwordx4 v[16:19], v[26:27], off
	global_load_dwordx4 v[20:23], v[84:85], off
	v_lshl_add_u64 v[86:87], v[24:25], 0, v[70:71]
	global_load_dwordx4 v[28:31], v[84:85], off offset:1024
	global_load_dwordx4 v[32:35], v[84:85], off offset:2048
	v_lshl_add_u64 v[90:91], v[24:25], 0, v[74:75]
	global_load_dwordx4 v[36:39], v[88:89], off
	global_load_dwordx4 v[24:27], v[90:91], off
	global_load_dwordx4 v[40:43], v[86:87], off
	global_load_dwordx4 v[44:47], v[84:85], off offset:3072
	v_mov_b32_e32 v71, v83
	s_mov_b32 s11, 1
.Lr0_nomods_B:
	v_add_u32_e32 v92, s12, v64
	s_nop 0
	v_readfirstlane_b32 s16, v92
	s_nop 3
	s_cmp_le_i32 s16, s14
	s_cselect_b32 s17, 1, 0
	s_cbranch_scc0 .Lr0_nonext_B
	v_add_u32_e32 v120, 0xffffc000, v92
	v_ashrrev_i32_e32 v124, 31, v92
	v_cmp_gt_i32_e32 vcc, s13, v92
	v_min_i32_e32 v125, 0x4000, v92
	v_ashrrev_i32_e32 v118, 13, v125
	v_cndmask_b32_e32 v121, 0, v124, vcc
	v_cndmask_b32_e32 v120, v120, v92, vcc
	v_cndmask_b32_e32 v123, v79, v80, vcc
	v_cndmask_b32_e32 v122, v81, v82, vcc
	v_lshlrev_b64 v[120:121], 12, v[120:121]
	v_lshl_add_u64 v[120:121], v[122:123], 0, v[120:121]
	v_lshl_add_u64 v[116:117], v[120:121], 0, v[66:67]
	global_load_dwordx4 v[60:63], v[116:117], off nt
	global_load_dwordx4 v[56:59], v[116:117], off offset:1024 nt
	global_load_dwordx4 v[52:55], v[116:117], off offset:2048 nt
	global_load_dwordx4 v[48:51], v[116:117], off offset:3072 nt
	s_cmp_lg_u32 s11, 0
	s_cbranch_scc1 .Lr0_w0_B
	s_cmp_lg_u32 s10, 0
	s_cbranch_scc1 .Lr0_w8_B
	s_waitcnt vmcnt(4)
	s_branch .Lr0_go_B

.Lr0_go_B:
	v_mul_f32_e32 v73, v113, v113
	v_mul_f32_e32 v75, v109, v109
	v_fmac_f32_e32 v73, v112, v112
	v_fmac_f32_e32 v75, v108, v108
	v_fmac_f32_e32 v73, v114, v114
	v_fmac_f32_e32 v75, v110, v110
	v_fmac_f32_e32 v73, v115, v115
	v_fmac_f32_e32 v75, v111, v111
	v_add_f32_e32 v73, v73, v75
	v_mul_f32_e32 v75, v105, v105
	v_fmac_f32_e32 v75, v104, v104
	v_fmac_f32_e32 v75, v106, v106
	v_fmac_f32_e32 v75, v107, v107
	v_add_f32_e32 v73, v73, v75
	v_mul_f32_e32 v75, v101, v101
	v_fmac_f32_e32 v75, v100, v100
	v_fmac_f32_e32 v75, v102, v102
	v_fmac_f32_e32 v75, v103, v103
	v_add_f32_e32 v73, v73, v75
	v_pk_add_f32 v[88:89], v[16:17], 1.0 op_sel_hi:[1,0]
	v_lshlrev_b64 v[86:87], 11, v[64:65]
	v_add_f32_dpp v73, v73, v73 row_ror:8 row_mask:0xf bank_mask:0xf bound_ctrl:1
	v_lshl_add_u64 v[86:87], v[68:69], 0, v[86:87]
	s_nop 0
	v_add_f32_dpp v73, v73, v73 row_ror:4 row_mask:0xf bank_mask:0xf bound_ctrl:1
	s_nop 0
	s_nop 0
	v_add_f32_dpp v73, v73, v73 row_ror:2 row_mask:0xf bank_mask:0xf bound_ctrl:1
	s_nop 1
	v_add_f32_dpp v73, v73, v73 row_ror:1 row_mask:0xf bank_mask:0xf bound_ctrl:1
	v_mov_b32_e32 v75, v73
	s_nop 1
	v_permlane32_swap_b32_e32 v73, v75
	v_add_f32_e32 v73, v73, v75
	ds_bpermute_b32 v75, v77, v73
	s_waitcnt lgkmcnt(0)
	v_add_f32_e32 v73, v73, v75
	v_fmamk_f32 v73, v73, 0x3a800000, v78
	v_rsq_f32_e32 v84, v73
	s_nop 0
	v_pk_mul_f32 v[112:113], v[112:113], v[84:85] op_sel_hi:[1,0]
	s_nop 0
	v_pk_mul_f32 v[112:113], v[0:1], v[112:113]
	v_pk_mul_f32 v[114:115], v[114:115], v[84:85] op_sel_hi:[1,0]
	v_pk_fma_f32 v[112:113], v[88:89], v[112:113], v[20:21]
	v_pk_mul_f32 v[114:115], v[2:3], v[114:115]
	v_pk_add_f32 v[88:89], v[18:19], 1.0 op_sel_hi:[1,0]
	v_cvt_pk_bf16_f32 v112, v112, v113
	v_pk_fma_f32 v[114:115], v[88:89], v[114:115], v[22:23]
	v_pk_mul_f32 v[108:109], v[108:109], v[84:85] op_sel_hi:[1,0]
	v_cvt_pk_bf16_f32 v113, v114, v115
	global_store_dwordx2 v[86:87], v[112:113], off
	v_pk_mul_f32 v[108:109], v[4:5], v[108:109]
	v_pk_add_f32 v[112:113], v[40:41], 1.0 op_sel_hi:[1,0]
	v_pk_mul_f32 v[110:111], v[110:111], v[84:85] op_sel_hi:[1,0]
	v_pk_fma_f32 v[108:109], v[112:113], v[108:109], v[28:29]
	v_pk_mul_f32 v[110:111], v[6:7], v[110:111]
	v_pk_add_f32 v[112:113], v[42:43], 1.0 op_sel_hi:[1,0]
	v_cvt_pk_bf16_f32 v108, v108, v109
	v_pk_fma_f32 v[110:111], v[112:113], v[110:111], v[30:31]
	v_pk_mul_f32 v[104:105], v[104:105], v[84:85] op_sel_hi:[1,0]
	v_cvt_pk_bf16_f32 v109, v110, v111
	global_store_dwordx2 v[86:87], v[108:109], off offset:512
	v_pk_mul_f32 v[104:105], v[8:9], v[104:105]
	v_pk_add_f32 v[108:109], v[36:37], 1.0 op_sel_hi:[1,0]
	v_pk_mul_f32 v[106:107], v[106:107], v[84:85] op_sel_hi:[1,0]
	v_pk_fma_f32 v[104:105], v[108:109], v[104:105], v[32:33]
	v_pk_mul_f32 v[106:107], v[10:11], v[106:107]
	v_pk_add_f32 v[108:109], v[38:39], 1.0 op_sel_hi:[1,0]
	v_cvt_pk_bf16_f32 v104, v104, v105
	v_pk_fma_f32 v[106:107], v[108:109], v[106:107], v[34:35]
	v_pk_mul_f32 v[100:101], v[100:101], v[84:85] op_sel_hi:[1,0]
	v_cvt_pk_bf16_f32 v105, v106, v107
	global_store_dwordx2 v[86:87], v[104:105], off offset:1024
	v_pk_mul_f32 v[100:101], v[12:13], v[100:101]
	v_pk_add_f32 v[104:105], v[24:25], 1.0 op_sel_hi:[1,0]
	v_pk_mul_f32 v[102:103], v[102:103], v[84:85] op_sel_hi:[1,0]
	v_pk_fma_f32 v[100:101], v[104:105], v[100:101], v[44:45]
	v_pk_mul_f32 v[102:103], v[14:15], v[102:103]
	v_pk_add_f32 v[104:105], v[26:27], 1.0 op_sel_hi:[1,0]
	v_cvt_pk_bf16_f32 v100, v100, v101
	v_pk_fma_f32 v[102:103], v[104:105], v[102:103], v[46:47]
	s_nop 0
	v_cvt_pk_bf16_f32 v101, v102, v103
	global_store_dwordx2 v[86:87], v[100:101], off offset:1536
	s_mov_b32 s10, 1
	v_mov_b32_e32 v64, v92
	v_mov_b32_e32 v83, v118
	s_cmp_lg_u32 s17, 0
	s_cbranch_scc0 .LBB0_161
	s_branch .Lr0_A

	.amdhsa_kernel _Z14fwd_megakernel6Params
		.amdhsa_group_segment_fixed_size 0
		.amdhsa_private_segment_fixed_size 0
		.amdhsa_kernarg_size 528
		.amdhsa_user_sgpr_count 2
		.amdhsa_user_sgpr_dispatch_ptr 0
		.amdhsa_user_sgpr_queue_ptr 0
		.amdhsa_user_sgpr_kernarg_segment_ptr 1
		.amdhsa_user_sgpr_dispatch_id 0
		.amdhsa_user_sgpr_kernarg_preload_length 0
		.amdhsa_user_sgpr_kernarg_preload_offset 0
		.amdhsa_user_sgpr_private_segment_size 0
		.amdhsa_uses_dynamic_stack 0
		.amdhsa_enable_private_segment 0
		.amdhsa_system_sgpr_workgroup_id_x 1
		.amdhsa_system_sgpr_workgroup_id_y 0
		.amdhsa_system_sgpr_workgroup_id_z 0
		.amdhsa_system_sgpr_workgroup_info 0
		.amdhsa_system_vgpr_workitem_id 2
		.amdhsa_next_free_vgpr 255
		.amdhsa_next_free_sgpr 102
		.amdhsa_accum_offset 256
		.amdhsa_reserve_vcc 1
		.amdhsa_float_round_mode_32 0
		.amdhsa_float_round_mode_16_64 0
		.amdhsa_float_denorm_mode_32 3
		.amdhsa_float_denorm_mode_16_64 3
		.amdhsa_dx10_clamp 1
		.amdhsa_ieee_mode 1
		.amdhsa_fp16_overflow 0
		.amdhsa_tg_split 0
		.amdhsa_exception_fp_ieee_invalid_op 0
		.amdhsa_exception_fp_denorm_src 0
		.amdhsa_exception_fp_ieee_div_zero 0
		.amdhsa_exception_fp_ieee_overflow 0
		.amdhsa_exception_fp_ieee_underflow 0
		.amdhsa_exception_fp_ieee_inexact 0
		.amdhsa_exception_int_div_zero 0
	.end_amdhsa_kernel

amdhsa.kernels:
  - .agpr_count:     0
    .args:
      - .offset:         0
        .size:           272
        .value_kind:     by_value
      - .offset:         272
        .size:           4
        .value_kind:     hidden_block_count_x
      - .offset:         276
        .size:           4
        .value_kind:     hidden_block_count_y
      - .offset:         280
        .size:           4
        .value_kind:     hidden_block_count_z
      - .offset:         284
        .size:           2
        .value_kind:     hidden_group_size_x
      - .offset:         286
        .size:           2
        .value_kind:     hidden_group_size_y
      - .offset:         288
        .size:           2
        .value_kind:     hidden_group_size_z
      - .offset:         290
        .size:           2
        .value_kind:     hidden_remainder_x
      - .offset:         292
        .size:           2
        .value_kind:     hidden_remainder_y
      - .offset:         294
        .size:           2
        .value_kind:     hidden_remainder_z
      - .offset:         312
        .size:           8
        .value_kind:     hidden_global_offset_x
      - .offset:         320
        .size:           8
        .value_kind:     hidden_global_offset_y
      - .offset:         328
        .size:           8
        .value_kind:     hidden_global_offset_z
      - .offset:         336
        .size:           2
        .value_kind:     hidden_grid_dims
      - .offset:         360
        .size:           8
        .value_kind:     hidden_multigrid_sync_arg
      - .offset:         392
        .size:           4
        .value_kind:     hidden_dynamic_lds_size
    .group_segment_fixed_size: 0
    .kernarg_segment_align: 8
    .kernarg_segment_size: 528
    .language:       OpenCL C
    .language_version:
      - 2
      - 0
    .max_flat_workgroup_size: 512
    .name:           _Z14fwd_megakernel6Params
    .private_segment_fixed_size: 0
    .sgpr_count:     108
    .sgpr_spill_count: 59
    .symbol:         _Z14fwd_megakernel6Params.kd
    .uniform_work_group_size: 1
    .uses_dynamic_stack: false
    .vgpr_count:     255
    .vgpr_spill_count: 0
    .wavefront_size: 64
